# w_out/ffn_down residual epilogue stores write-through (sc1): they are the last stores before the grid barrier, so the XCD leader's L2 write-back has less to flush
# baseline (speedup 1.0000x reference)
.Lepi_bd:
	s_nop 1
	s_lshl_b32 s16, s24, 12
	s_lshl_b32 s17, s42, 10
	s_add_u32 s16, s16, s17
	s_add_u32 s12, s12, s16
	s_addc_u32 s13, s13, 0
	s_add_u32 s14, s14, s16
	s_addc_u32 s15, s15, 0
	v_lshlrev_b32_e32 v224, 12, v143
	v_lshl_add_u32 v224, v218, 2, v224
	v_add_u32_e32 v225, 0x0, v224
	global_load_dwordx4 v[150:153], v225, s[14:15] offset:0
	v_add_u32_e32 v239, 0x10000, v224
	global_load_dwordx4 v[154:157], v239, s[14:15] offset:0
	v_add_u32_e32 v225, 0x20000, v224
	global_load_dwordx4 v[158:161], v225, s[14:15] offset:0
	v_add_u32_e32 v239, 0x30000, v224
	global_load_dwordx4 v[162:165], v239, s[14:15] offset:0
	v_add_u32_e32 v225, 0x80000, v224
	global_load_dwordx4 v[166:169], v225, s[14:15] offset:0
	v_add_u32_e32 v239, 0x90000, v224
	global_load_dwordx4 v[170:173], v239, s[14:15] offset:0
	v_add_u32_e32 v225, 0xa0000, v224
	global_load_dwordx4 v[174:177], v225, s[14:15] offset:0
	v_add_u32_e32 v239, 0xb0000, v224
	global_load_dwordx4 v[178:181], v239, s[14:15] offset:0
	v_add_u32_e32 v225, 0x0, v224
	global_load_dwordx4 v[182:185], v225, s[14:15] offset:64
	v_add_u32_e32 v239, 0x10000, v224
	global_load_dwordx4 v[186:189], v239, s[14:15] offset:64
	v_add_u32_e32 v225, 0x20000, v224
	global_load_dwordx4 v[190:193], v225, s[14:15] offset:64
	v_add_u32_e32 v239, 0x30000, v224
	global_load_dwordx4 v[194:197], v239, s[14:15] offset:64
	s_waitcnt vmcnt(8)
	v_fma_f32 v150, v126, v130, v150
	v_fma_f32 v151, v127, v131, v151
	v_fma_f32 v152, v128, v132, v152
	v_fma_f32 v153, v129, v133, v153
	v_fma_f32 v154, v118, v130, v154
	v_fma_f32 v155, v119, v131, v155
	v_fma_f32 v156, v120, v132, v156
	v_fma_f32 v157, v121, v133, v157
	v_fma_f32 v158, v110, v130, v158
	v_fma_f32 v159, v111, v131, v159
	v_fma_f32 v160, v112, v132, v160
	v_fma_f32 v161, v113, v133, v161
	v_fma_f32 v162, v102, v130, v162
	v_fma_f32 v163, v103, v131, v163
	v_fma_f32 v164, v104, v132, v164
	v_fma_f32 v165, v105, v133, v165
	v_add_u32_e32 v242, 0x0, v224
	global_store_dwordx4 v242, v[150:153], s[12:13] offset:0 sc1
	v_add_u32_e32 v245, 0x10000, v224
	global_store_dwordx4 v245, v[154:157], s[12:13] offset:0 sc1
	v_add_u32_e32 v242, 0x20000, v224
	global_store_dwordx4 v242, v[158:161], s[12:13] offset:0 sc1
	v_add_u32_e32 v245, 0x30000, v224
	global_store_dwordx4 v245, v[162:165], s[12:13] offset:0 sc1
	global_load_dword v227, v0, s[0:1] offset:64
	global_load_dword v230, v0, s[0:1] offset:68
	global_load_dword v233, v0, s[0:1] offset:72
	global_load_dword v236, v0, s[0:1] offset:76
	v_add_u32_e32 v225, 0x80000, v224
	global_load_dwordx4 v[150:153], v225, s[14:15] offset:64
	v_add_u32_e32 v239, 0x90000, v224
	global_load_dwordx4 v[154:157], v239, s[14:15] offset:64
	v_add_u32_e32 v225, 0xa0000, v224
	global_load_dwordx4 v[158:161], v225, s[14:15] offset:64
	v_add_u32_e32 v239, 0xb0000, v224
	global_load_dwordx4 v[162:165], v239, s[14:15] offset:64
	s_waitcnt vmcnt(16)
	v_fma_f32 v166, v94, v130, v166
	v_fma_f32 v167, v95, v131, v167
	v_fma_f32 v168, v96, v132, v168
	v_fma_f32 v169, v97, v133, v169
	v_fma_f32 v170, v86, v130, v170
	v_fma_f32 v171, v87, v131, v171
	v_fma_f32 v172, v88, v132, v172
	v_fma_f32 v173, v89, v133, v173
	v_fma_f32 v174, v78, v130, v174
	v_fma_f32 v175, v79, v131, v175
	v_fma_f32 v176, v80, v132, v176
	v_fma_f32 v177, v81, v133, v177
	v_fma_f32 v178, v70, v130, v178
	v_fma_f32 v179, v71, v131, v179
	v_fma_f32 v180, v72, v132, v180
	v_fma_f32 v181, v73, v133, v181
	v_add_u32_e32 v242, 0x80000, v224
	global_store_dwordx4 v242, v[166:169], s[12:13] offset:0 sc1
	v_add_u32_e32 v245, 0x90000, v224
	global_store_dwordx4 v245, v[170:173], s[12:13] offset:0 sc1
	v_add_u32_e32 v242, 0xa0000, v224
	global_store_dwordx4 v242, v[174:177], s[12:13] offset:0 sc1
	v_add_u32_e32 v245, 0xb0000, v224
	global_store_dwordx4 v245, v[178:181], s[12:13] offset:0 sc1
	v_add_u32_e32 v225, 0x0, v224
	global_load_dwordx4 v[166:169], v225, s[14:15] offset:512
	v_add_u32_e32 v239, 0x10000, v224
	global_load_dwordx4 v[170:173], v239, s[14:15] offset:512
	v_add_u32_e32 v225, 0x20000, v224
	global_load_dwordx4 v[174:177], v225, s[14:15] offset:512
	v_add_u32_e32 v239, 0x30000, v224
	global_load_dwordx4 v[178:181], v239, s[14:15] offset:512
	s_waitcnt vmcnt(12)
	v_fma_f32 v182, v122, v227, v182
	v_fma_f32 v183, v123, v230, v183
	v_fma_f32 v184, v124, v233, v184
	v_fma_f32 v185, v125, v236, v185
	v_fma_f32 v186, v114, v227, v186
	v_fma_f32 v187, v115, v230, v187
	v_fma_f32 v188, v116, v233, v188
	v_fma_f32 v189, v117, v236, v189
	v_fma_f32 v190, v106, v227, v190
	v_fma_f32 v191, v107, v230, v191
	v_fma_f32 v192, v108, v233, v192
	v_fma_f32 v193, v109, v236, v193
	v_fma_f32 v194, v98, v227, v194
	v_fma_f32 v195, v99, v230, v195
	v_fma_f32 v196, v100, v233, v196
	v_fma_f32 v197, v101, v236, v197
	v_add_u32_e32 v242, 0x0, v224
	global_store_dwordx4 v242, v[182:185], s[12:13] offset:64 sc1
	v_add_u32_e32 v245, 0x10000, v224
	global_store_dwordx4 v245, v[186:189], s[12:13] offset:64 sc1
	v_add_u32_e32 v242, 0x20000, v224
	global_store_dwordx4 v242, v[190:193], s[12:13] offset:64 sc1
	v_add_u32_e32 v245, 0x30000, v224
	global_store_dwordx4 v245, v[194:197], s[12:13] offset:64 sc1
	global_load_dwordx4 v[130:133], v0, s[0:1] offset:512
	v_add_u32_e32 v225, 0x80000, v224
	global_load_dwordx4 v[182:185], v225, s[14:15] offset:512
	v_add_u32_e32 v239, 0x90000, v224
	global_load_dwordx4 v[186:189], v239, s[14:15] offset:512
	v_add_u32_e32 v225, 0xa0000, v224
	global_load_dwordx4 v[190:193], v225, s[14:15] offset:512
	v_add_u32_e32 v239, 0xb0000, v224
	global_load_dwordx4 v[194:197], v239, s[14:15] offset:512
	s_waitcnt vmcnt(17)
	v_fma_f32 v150, v90, v227, v150
	v_fma_f32 v151, v91, v230, v151
	v_fma_f32 v152, v92, v233, v152
	v_fma_f32 v153, v93, v236, v153
	v_fma_f32 v154, v82, v227, v154
	v_fma_f32 v155, v83, v230, v155
	v_fma_f32 v156, v84, v233, v156
	v_fma_f32 v157, v85, v236, v157
	v_fma_f32 v158, v74, v227, v158
	v_fma_f32 v159, v75, v230, v159
	v_fma_f32 v160, v76, v233, v160
	v_fma_f32 v161, v77, v236, v161
	v_fma_f32 v162, v66, v227, v162
	v_fma_f32 v163, v67, v230, v163
	v_fma_f32 v164, v68, v233, v164
	v_fma_f32 v165, v69, v236, v165
	v_add_u32_e32 v242, 0x80000, v224
	global_store_dwordx4 v242, v[150:153], s[12:13] offset:64 sc1
	v_add_u32_e32 v245, 0x90000, v224
	global_store_dwordx4 v245, v[154:157], s[12:13] offset:64 sc1
	v_add_u32_e32 v242, 0xa0000, v224
	global_store_dwordx4 v242, v[158:161], s[12:13] offset:64 sc1
	v_add_u32_e32 v245, 0xb0000, v224
	global_store_dwordx4 v245, v[162:165], s[12:13] offset:64 sc1
	v_add_u32_e32 v225, 0x0, v224
	global_load_dwordx4 v[150:153], v225, s[14:15] offset:576
	v_add_u32_e32 v239, 0x10000, v224
	global_load_dwordx4 v[154:157], v239, s[14:15] offset:576
	v_add_u32_e32 v225, 0x20000, v224
	global_load_dwordx4 v[158:161], v225, s[14:15] offset:576
	v_add_u32_e32 v239, 0x30000, v224
	global_load_dwordx4 v[162:165], v239, s[14:15] offset:576
	s_waitcnt vmcnt(12)
	v_fma_f32 v166, v62, v130, v166
	v_fma_f32 v167, v63, v131, v167
	v_fma_f32 v168, v64, v132, v168
	v_fma_f32 v169, v65, v133, v169
	v_fma_f32 v170, v54, v130, v170
	v_fma_f32 v171, v55, v131, v171
	v_fma_f32 v172, v56, v132, v172
	v_fma_f32 v173, v57, v133, v173
	v_fma_f32 v174, v46, v130, v174
	v_fma_f32 v175, v47, v131, v175
	v_fma_f32 v176, v48, v132, v176
	v_fma_f32 v177, v49, v133, v177
	v_fma_f32 v178, v38, v130, v178
	v_fma_f32 v179, v39, v131, v179
	v_fma_f32 v180, v40, v132, v180
	v_fma_f32 v181, v41, v133, v181
	v_add_u32_e32 v242, 0x0, v224
	global_store_dwordx4 v242, v[166:169], s[12:13] offset:512 sc1
	v_add_u32_e32 v245, 0x10000, v224
	global_store_dwordx4 v245, v[170:173], s[12:13] offset:512 sc1
	v_add_u32_e32 v242, 0x20000, v224
	global_store_dwordx4 v242, v[174:177], s[12:13] offset:512 sc1
	v_add_u32_e32 v245, 0x30000, v224
	global_store_dwordx4 v245, v[178:181], s[12:13] offset:512 sc1
	global_load_dword v227, v0, s[0:1] offset:576
	global_load_dword v230, v0, s[0:1] offset:580
	global_load_dword v233, v0, s[0:1] offset:584
	global_load_dword v236, v0, s[0:1] offset:588
	v_add_u32_e32 v225, 0x80000, v224
	global_load_dwordx4 v[166:169], v225, s[14:15] offset:576
	v_add_u32_e32 v239, 0x90000, v224
	global_load_dwordx4 v[170:173], v239, s[14:15] offset:576
	v_add_u32_e32 v225, 0xa0000, v224
	global_load_dwordx4 v[174:177], v225, s[14:15] offset:576
	v_add_u32_e32 v239, 0xb0000, v224
	global_load_dwordx4 v[178:181], v239, s[14:15] offset:576
	s_waitcnt vmcnt(20)
	v_fma_f32 v182, v30, v130, v182
	v_fma_f32 v183, v31, v131, v183
	v_fma_f32 v184, v32, v132, v184
	v_fma_f32 v185, v33, v133, v185
	v_fma_f32 v186, v22, v130, v186
	v_fma_f32 v187, v23, v131, v187
	v_fma_f32 v188, v24, v132, v188
	v_fma_f32 v189, v25, v133, v189
	v_fma_f32 v190, v14, v130, v190
	v_fma_f32 v191, v15, v131, v191
	v_fma_f32 v192, v16, v132, v192
	v_fma_f32 v193, v17, v133, v193
	v_fma_f32 v194, v6, v130, v194
	v_fma_f32 v195, v7, v131, v195
	v_fma_f32 v196, v8, v132, v196
	v_fma_f32 v197, v9, v133, v197
	v_add_u32_e32 v242, 0x80000, v224
	global_store_dwordx4 v242, v[182:185], s[12:13] offset:512 sc1
	v_add_u32_e32 v245, 0x90000, v224
	global_store_dwordx4 v245, v[186:189], s[12:13] offset:512 sc1
	v_add_u32_e32 v242, 0xa0000, v224
	global_store_dwordx4 v242, v[190:193], s[12:13] offset:512 sc1
	v_add_u32_e32 v245, 0xb0000, v224
	global_store_dwordx4 v245, v[194:197], s[12:13] offset:512 sc1
	s_waitcnt vmcnt(8)
	v_fma_f32 v150, v58, v227, v150
	v_fma_f32 v151, v59, v230, v151
	v_fma_f32 v152, v60, v233, v152
	v_fma_f32 v153, v61, v236, v153
	v_fma_f32 v154, v50, v227, v154
	v_fma_f32 v155, v51, v230, v155
	v_fma_f32 v156, v52, v233, v156
	v_fma_f32 v157, v53, v236, v157
	v_fma_f32 v158, v42, v227, v158
	v_fma_f32 v159, v43, v230, v159
	v_fma_f32 v160, v44, v233, v160
	v_fma_f32 v161, v45, v236, v161
	v_fma_f32 v162, v34, v227, v162
	v_fma_f32 v163, v35, v230, v163
	v_fma_f32 v164, v36, v233, v164
	v_fma_f32 v165, v37, v236, v165
	v_add_u32_e32 v242, 0x0, v224
	global_store_dwordx4 v242, v[150:153], s[12:13] offset:576 sc1
	v_add_u32_e32 v245, 0x10000, v224
	global_store_dwordx4 v245, v[154:157], s[12:13] offset:576 sc1
	v_add_u32_e32 v242, 0x20000, v224
	global_store_dwordx4 v242, v[158:161], s[12:13] offset:576 sc1
	v_add_u32_e32 v245, 0x30000, v224
	global_store_dwordx4 v245, v[162:165], s[12:13] offset:576 sc1
	s_waitcnt vmcnt(8)
	v_fma_f32 v166, v26, v227, v166
	v_fma_f32 v167, v27, v230, v167
	v_fma_f32 v168, v28, v233, v168
	v_fma_f32 v169, v29, v236, v169
	v_fma_f32 v170, v18, v227, v170
	v_fma_f32 v171, v19, v230, v171
	v_fma_f32 v172, v20, v233, v172
	v_fma_f32 v173, v21, v236, v173
	v_fma_f32 v174, v10, v227, v174
	v_fma_f32 v175, v11, v230, v175
	v_fma_f32 v176, v12, v233, v176
	v_fma_f32 v177, v13, v236, v177
	v_fma_f32 v178, v2, v227, v178
	v_fma_f32 v179, v3, v230, v179
	v_fma_f32 v180, v4, v233, v180
	v_fma_f32 v181, v5, v236, v181
	v_add_u32_e32 v242, 0x80000, v224
	global_store_dwordx4 v242, v[166:169], s[12:13] offset:576 sc1
	v_add_u32_e32 v245, 0x90000, v224
	global_store_dwordx4 v245, v[170:173], s[12:13] offset:576 sc1
	v_add_u32_e32 v242, 0xa0000, v224
	global_store_dwordx4 v242, v[174:177], s[12:13] offset:576 sc1
	v_add_u32_e32 v245, 0xb0000, v224
	global_store_dwordx4 v245, v[178:181], s[12:13] offset:576 sc1
	s_mov_b64 s[0:1], 0
